# S5 scan: removed dead LDS-base adds and precomputed first-step partial products; scan state kept in place (14 fewer instructions per chunk)
# speedup vs baseline: 1.0238x; 1.0017x over previous
.LBB0_99:
	s_or_b64 exec, exec, s[20:21]
	s_sub_i32 s20, s34, 32
	v_add_u32_e32 v0, 32, v210
	v_mov_b32_e32 v2, s20
	v_cndmask_b32_e64 v0, v0, v2, s[40:41]
	s_waitcnt lgkmcnt(0)
	ds_read_b128 v[14:17], v208
	ds_read_b128 v[30:33], v208 offset:4352
	ds_read_b128 v[18:21], v208 offset:64
	ds_read_b128 v[34:37], v208 offset:4416
	ds_read_b128 v[22:25], v208 offset:128
	ds_read_b128 v[38:41], v208 offset:4480
	ds_read_b128 v[26:29], v208 offset:192
	ds_read_b128 v[42:45], v208 offset:4544
	s_movk_i32 s20, 0x3000
	s_add_i32 s28, s28, 1
	s_add_i32 s34, s34, 16
	v_add_u32_e32 v210, -16, v210
	s_waitcnt lgkmcnt(6)
	v_mfma_f32_16x16x32_bf16 v[2:5], v[14:17], v[82:85], 0
	v_mfma_f32_16x16x32_bf16 v[6:9], v[30:33], v[82:85], 0
	s_waitcnt lgkmcnt(4)
	v_mfma_f32_16x16x32_bf16 v[2:5], v[18:21], v[86:89], v[2:5]
	v_mfma_f32_16x16x32_bf16 v[6:9], v[34:37], v[86:89], v[6:9]
	s_waitcnt lgkmcnt(2)
	v_mfma_f32_16x16x32_bf16 v[2:5], v[22:25], v[90:93], v[2:5]
	v_mfma_f32_16x16x32_bf16 v[6:9], v[38:41], v[90:93], v[6:9]
	s_waitcnt lgkmcnt(0)
	v_mfma_f32_16x16x32_bf16 v[2:5], v[26:29], v[94:97], v[2:5]
	v_mfma_f32_16x16x32_bf16 v[6:9], v[42:45], v[94:97], v[6:9]
	s_nop 3
	v_ashrrev_i32_e32 v11, 31, v0
	v_or_b32_e32 v10, v0, v140
	v_lshl_add_u64 v[12:13], v[10:11], 0, v[164:165]
	v_lshlrev_b64 v[12:13], 12, v[12:13]
	v_lshl_add_u64 v[12:13], v[162:163], 0, v[12:13]
	v_add_co_u32_e32 v14, vcc, s23, v12
	global_store_dword v[12:13], v2, off
	s_nop 0
	v_addc_co_u32_e32 v15, vcc, 0, v13, vcc
	v_add_co_u32_e32 v2, vcc, s20, v12
	global_store_dword v[14:15], v3, off offset:-4096
	global_store_dword v[14:15], v4, off
	v_addc_co_u32_e32 v3, vcc, 0, v13, vcc
	global_store_dword v[2:3], v5, off
	v_lshl_add_u64 v[2:3], v[10:11], 0, v[166:167]
	v_lshlrev_b64 v[2:3], 12, v[2:3]
	v_lshl_add_u64 v[2:3], v[162:163], 0, v[2:3]
	v_add_co_u32_e32 v4, vcc, s23, v2
	global_store_dword v[2:3], v6, off
	s_nop 0
	v_addc_co_u32_e32 v5, vcc, 0, v3, vcc
	v_add_co_u32_e32 v2, vcc, 0x3000, v2
	global_store_dword v[4:5], v7, off offset:-4096
	global_store_dword v[4:5], v8, off
	v_addc_co_u32_e32 v3, vcc, 0, v3, vcc
	global_store_dword v[2:3], v9, off
	s_waitcnt vmcnt(8)
	v_mov_b64_e32 v[8:9], v[102:103]
	v_mov_b64_e32 v[4:5], v[98:99]
	v_cmp_eq_u32_e32 vcc, s28, v149
	v_mov_b64_e32 v[10:11], v[104:105]
	v_mov_b64_e32 v[6:7], v[100:101]
	v_mov_b64_e32 v[102:103], v[106:107]
	v_mov_b64_e32 v[98:99], v[110:111]
	s_or_b64 s[2:3], vcc, s[2:3]
	v_mov_b64_e32 v[104:105], v[108:109]
	v_mov_b64_e32 v[100:101], v[112:113]
	s_andn2_b64 exec, exec, s[2:3]
	s_cbranch_execz .LBB0_106

.LBB0_102:
	s_or_b64 exec, exec, s[20:21]
	v_cvt_pk_bf16_f32 v18, v8, v9
	v_cvt_pk_bf16_f32 v19, v10, v11
	v_cvt_pk_bf16_f32 v20, v4, v5
	v_cvt_pk_bf16_f32 v21, v6, v7
	s_nop 1
	v_mfma_f32_32x32x16_bf16 v[34:49], v[18:21], v[66:69], 0
	v_mfma_f32_32x32x16_bf16 v[2:17], v[18:21], v[70:73], 0
	v_mfma_f32_32x32x16_bf16 v[50:65], v[18:21], v[74:77], 0
	v_mfma_f32_32x32x16_bf16 v[18:33], v[18:21], v[78:81], 0
	s_and_saveexec_b64 s[20:21], s[42:43]
	s_xor_b64 s[20:21], exec, s[20:21]
	s_cbranch_execz .LBB0_104
	s_nop 7
	v_fmac_f32_e32 v49, v152, v182
	v_fmac_f32_e32 v65, v152, v178
	v_fmac_f32_e32 v17, v154, v180
	v_fmac_f32_e32 v33, v154, v176
	v_fma_f32 v49, -v153, v178, v49
	v_fmac_f32_e32 v65, v153, v182
	v_fma_f32 v17, -v155, v176, v17
	v_fmac_f32_e32 v33, v155, v180
	v_cvt_pk_bf16_f32 v184, v49, v65
	v_cvt_pk_bf16_f32 v185, v17, v33
	ds_write_b32 v207, v184 offset:4080
	ds_write_b32 v207, v185 offset:4208
	v_fmac_f32_e32 v48, v152, v49
	v_fmac_f32_e32 v64, v152, v65
	v_fmac_f32_e32 v16, v154, v17
	v_fmac_f32_e32 v32, v154, v33
	v_fma_f32 v48, -v153, v65, v48
	v_fmac_f32_e32 v64, v153, v49
	v_fma_f32 v16, -v155, v33, v16
	v_fmac_f32_e32 v32, v155, v17
	v_cvt_pk_bf16_f32 v184, v48, v64
	v_cvt_pk_bf16_f32 v185, v16, v32
	ds_write_b32 v207, v184 offset:3808
	ds_write_b32 v207, v185 offset:3936
	v_fmac_f32_e32 v47, v152, v48
	v_fmac_f32_e32 v63, v152, v64
	v_fmac_f32_e32 v15, v154, v16
	v_fmac_f32_e32 v31, v154, v32
	v_fma_f32 v47, -v153, v64, v47
	v_fmac_f32_e32 v63, v153, v48
	v_fma_f32 v15, -v155, v32, v15
	v_fmac_f32_e32 v31, v155, v16
	v_cvt_pk_bf16_f32 v184, v47, v63
	v_cvt_pk_bf16_f32 v185, v15, v31
	ds_write_b32 v207, v184 offset:3536
	ds_write_b32 v207, v185 offset:3664
	v_fmac_f32_e32 v46, v152, v47
	v_fmac_f32_e32 v62, v152, v63
	v_fmac_f32_e32 v14, v154, v15
	v_fmac_f32_e32 v30, v154, v31
	v_fma_f32 v46, -v153, v63, v46
	v_fmac_f32_e32 v62, v153, v47
	v_fma_f32 v14, -v155, v31, v14
	v_fmac_f32_e32 v30, v155, v15
	v_cvt_pk_bf16_f32 v184, v46, v62
	v_cvt_pk_bf16_f32 v185, v14, v30
	ds_write_b32 v207, v184 offset:3264
	ds_write_b32 v207, v185 offset:3392
	v_fmac_f32_e32 v45, v152, v46
	v_fmac_f32_e32 v61, v152, v62
	v_fmac_f32_e32 v13, v154, v14
	v_fmac_f32_e32 v29, v154, v30
	v_fma_f32 v45, -v153, v62, v45
	v_fmac_f32_e32 v61, v153, v46
	v_fma_f32 v13, -v155, v30, v13
	v_fmac_f32_e32 v29, v155, v14
	v_cvt_pk_bf16_f32 v184, v45, v61
	v_cvt_pk_bf16_f32 v185, v13, v29
	ds_write_b32 v207, v184 offset:2992
	ds_write_b32 v207, v185 offset:3120
	v_fmac_f32_e32 v44, v152, v45
	v_fmac_f32_e32 v60, v152, v61
	v_fmac_f32_e32 v12, v154, v13
	v_fmac_f32_e32 v28, v154, v29
	v_fma_f32 v44, -v153, v61, v44
	v_fmac_f32_e32 v60, v153, v45
	v_fma_f32 v12, -v155, v29, v12
	v_fmac_f32_e32 v28, v155, v13
	v_cvt_pk_bf16_f32 v184, v44, v60
	v_cvt_pk_bf16_f32 v185, v12, v28
	ds_write_b32 v207, v184 offset:2720
	ds_write_b32 v207, v185 offset:2848
	v_fmac_f32_e32 v43, v152, v44
	v_fmac_f32_e32 v59, v152, v60
	v_fmac_f32_e32 v11, v154, v12
	v_fmac_f32_e32 v27, v154, v28
	v_fma_f32 v43, -v153, v60, v43
	v_fmac_f32_e32 v59, v153, v44
	v_fma_f32 v11, -v155, v28, v11
	v_fmac_f32_e32 v27, v155, v12
	v_cvt_pk_bf16_f32 v184, v43, v59
	v_cvt_pk_bf16_f32 v185, v11, v27
	ds_write_b32 v207, v184 offset:2448
	ds_write_b32 v207, v185 offset:2576
	v_fmac_f32_e32 v42, v152, v43
	v_fmac_f32_e32 v58, v152, v59
	v_fmac_f32_e32 v10, v154, v11
	v_fmac_f32_e32 v26, v154, v27
	v_fma_f32 v42, -v153, v59, v42
	v_fmac_f32_e32 v58, v153, v43
	v_fma_f32 v10, -v155, v27, v10
	v_fmac_f32_e32 v26, v155, v11
	v_cvt_pk_bf16_f32 v184, v42, v58
	v_cvt_pk_bf16_f32 v185, v10, v26
	ds_write_b32 v207, v184 offset:2176
	ds_write_b32 v207, v185 offset:2304
	v_fmac_f32_e32 v41, v152, v42
	v_fmac_f32_e32 v57, v152, v58
	v_fmac_f32_e32 v9, v154, v10
	v_fmac_f32_e32 v25, v154, v26
	v_fma_f32 v41, -v153, v58, v41
	v_fmac_f32_e32 v57, v153, v42
	v_fma_f32 v9, -v155, v26, v9
	v_fmac_f32_e32 v25, v155, v10
	v_cvt_pk_bf16_f32 v184, v41, v57
	v_cvt_pk_bf16_f32 v185, v9, v25
	ds_write_b32 v207, v184 offset:1904
	ds_write_b32 v207, v185 offset:2032
	v_fmac_f32_e32 v40, v152, v41
	v_fmac_f32_e32 v56, v152, v57
	v_fmac_f32_e32 v8, v154, v9
	v_fmac_f32_e32 v24, v154, v25
	v_fma_f32 v40, -v153, v57, v40
	v_fmac_f32_e32 v56, v153, v41
	v_fma_f32 v8, -v155, v25, v8
	v_fmac_f32_e32 v24, v155, v9
	v_cvt_pk_bf16_f32 v184, v40, v56
	v_cvt_pk_bf16_f32 v185, v8, v24
	ds_write_b32 v207, v184 offset:1632
	ds_write_b32 v207, v185 offset:1760
	v_fmac_f32_e32 v39, v152, v40
	v_fmac_f32_e32 v55, v152, v56
	v_fmac_f32_e32 v7, v154, v8
	v_fmac_f32_e32 v23, v154, v24
	v_fma_f32 v39, -v153, v56, v39
	v_fmac_f32_e32 v55, v153, v40
	v_fma_f32 v7, -v155, v24, v7
	v_fmac_f32_e32 v23, v155, v8
	v_cvt_pk_bf16_f32 v184, v39, v55
	v_cvt_pk_bf16_f32 v185, v7, v23
	ds_write_b32 v207, v184 offset:1360
	ds_write_b32 v207, v185 offset:1488
	v_fmac_f32_e32 v38, v152, v39
	v_fmac_f32_e32 v54, v152, v55
	v_fmac_f32_e32 v6, v154, v7
	v_fmac_f32_e32 v22, v154, v23
	v_fma_f32 v38, -v153, v55, v38
	v_fmac_f32_e32 v54, v153, v39
	v_fma_f32 v6, -v155, v23, v6
	v_fmac_f32_e32 v22, v155, v7
	v_cvt_pk_bf16_f32 v184, v38, v54
	v_cvt_pk_bf16_f32 v185, v6, v22
	ds_write_b32 v207, v184 offset:1088
	ds_write_b32 v207, v185 offset:1216
	v_fmac_f32_e32 v37, v152, v38
	v_fmac_f32_e32 v53, v152, v54
	v_fmac_f32_e32 v5, v154, v6
	v_fmac_f32_e32 v21, v154, v22
	v_fma_f32 v37, -v153, v54, v37
	v_fmac_f32_e32 v53, v153, v38
	v_fma_f32 v5, -v155, v22, v5
	v_fmac_f32_e32 v21, v155, v6
	v_cvt_pk_bf16_f32 v184, v37, v53
	v_cvt_pk_bf16_f32 v185, v5, v21
	ds_write_b32 v207, v184 offset:816
	ds_write_b32 v207, v185 offset:944
	v_fmac_f32_e32 v36, v152, v37
	v_fmac_f32_e32 v52, v152, v53
	v_fmac_f32_e32 v4, v154, v5
	v_fmac_f32_e32 v20, v154, v21
	v_fma_f32 v36, -v153, v53, v36
	v_fmac_f32_e32 v52, v153, v37
	v_fma_f32 v4, -v155, v21, v4
	v_fmac_f32_e32 v20, v155, v5
	v_cvt_pk_bf16_f32 v184, v36, v52
	v_cvt_pk_bf16_f32 v185, v4, v20
	ds_write_b32 v207, v184 offset:544
	ds_write_b32 v207, v185 offset:672
	v_fmac_f32_e32 v35, v152, v36
	v_fmac_f32_e32 v51, v152, v52
	v_fmac_f32_e32 v3, v154, v4
	v_fmac_f32_e32 v19, v154, v20
	v_fma_f32 v35, -v153, v52, v35
	v_fmac_f32_e32 v51, v153, v36
	v_fma_f32 v3, -v155, v20, v3
	v_fmac_f32_e32 v19, v155, v4
	v_cvt_pk_bf16_f32 v184, v35, v51
	v_cvt_pk_bf16_f32 v185, v3, v19
	ds_write_b32 v207, v184 offset:272
	ds_write_b32 v207, v185 offset:400
	v_fmac_f32_e32 v34, v152, v35
	v_fmac_f32_e32 v50, v152, v51
	v_fmac_f32_e32 v2, v154, v3
	v_fmac_f32_e32 v18, v154, v19
	v_fma_f32 v34, -v153, v51, v34
	v_fmac_f32_e32 v50, v153, v35
	v_fma_f32 v2, -v155, v19, v2
	v_fmac_f32_e32 v18, v155, v3
	v_cvt_pk_bf16_f32 v184, v34, v50
	v_cvt_pk_bf16_f32 v185, v2, v18
	ds_write_b32 v207, v184 offset:0
	ds_write_b32 v207, v185 offset:128
	v_mov_b32_e32 v182, v34
	v_mov_b32_e32 v178, v50
	v_mov_b32_e32 v180, v2
	v_mov_b32_e32 v176, v18
.LBB0_104:
	s_andn2_saveexec_b64 s[20:21], s[20:21]
	s_cbranch_execz .LBB0_99
	s_nop 7
	v_fmac_f32_e32 v34, v152, v182
	v_fmac_f32_e32 v50, v152, v178
	v_fmac_f32_e32 v2, v154, v180
	v_fmac_f32_e32 v18, v154, v176
	v_fma_f32 v34, -v153, v178, v34
	v_fmac_f32_e32 v50, v153, v182
	v_fma_f32 v2, -v155, v176, v2
	v_fmac_f32_e32 v18, v155, v180
	v_cvt_pk_bf16_f32 v184, v34, v50
	v_cvt_pk_bf16_f32 v185, v2, v18
	ds_write_b32 v207, v184 offset:0
	ds_write_b32 v207, v185 offset:128
	v_fmac_f32_e32 v35, v152, v34
	v_fmac_f32_e32 v51, v152, v50
	v_fmac_f32_e32 v3, v154, v2
	v_fmac_f32_e32 v19, v154, v18
	v_fma_f32 v35, -v153, v50, v35
	v_fmac_f32_e32 v51, v153, v34
	v_fma_f32 v3, -v155, v18, v3
	v_fmac_f32_e32 v19, v155, v2
	v_cvt_pk_bf16_f32 v184, v35, v51
	v_cvt_pk_bf16_f32 v185, v3, v19
	ds_write_b32 v207, v184 offset:272
	ds_write_b32 v207, v185 offset:400
	v_fmac_f32_e32 v36, v152, v35
	v_fmac_f32_e32 v52, v152, v51
	v_fmac_f32_e32 v4, v154, v3
	v_fmac_f32_e32 v20, v154, v19
	v_fma_f32 v36, -v153, v51, v36
	v_fmac_f32_e32 v52, v153, v35
	v_fma_f32 v4, -v155, v19, v4
	v_fmac_f32_e32 v20, v155, v3
	v_cvt_pk_bf16_f32 v184, v36, v52
	v_cvt_pk_bf16_f32 v185, v4, v20
	ds_write_b32 v207, v184 offset:544
	ds_write_b32 v207, v185 offset:672
	v_fmac_f32_e32 v37, v152, v36
	v_fmac_f32_e32 v53, v152, v52
	v_fmac_f32_e32 v5, v154, v4
	v_fmac_f32_e32 v21, v154, v20
	v_fma_f32 v37, -v153, v52, v37
	v_fmac_f32_e32 v53, v153, v36
	v_fma_f32 v5, -v155, v20, v5
	v_fmac_f32_e32 v21, v155, v4
	v_cvt_pk_bf16_f32 v184, v37, v53
	v_cvt_pk_bf16_f32 v185, v5, v21
	ds_write_b32 v207, v184 offset:816
	ds_write_b32 v207, v185 offset:944
	v_fmac_f32_e32 v38, v152, v37
	v_fmac_f32_e32 v54, v152, v53
	v_fmac_f32_e32 v6, v154, v5
	v_fmac_f32_e32 v22, v154, v21
	v_fma_f32 v38, -v153, v53, v38
	v_fmac_f32_e32 v54, v153, v37
	v_fma_f32 v6, -v155, v21, v6
	v_fmac_f32_e32 v22, v155, v5
	v_cvt_pk_bf16_f32 v184, v38, v54
	v_cvt_pk_bf16_f32 v185, v6, v22
	ds_write_b32 v207, v184 offset:1088
	ds_write_b32 v207, v185 offset:1216
	v_fmac_f32_e32 v39, v152, v38
	v_fmac_f32_e32 v55, v152, v54
	v_fmac_f32_e32 v7, v154, v6
	v_fmac_f32_e32 v23, v154, v22
	v_fma_f32 v39, -v153, v54, v39
	v_fmac_f32_e32 v55, v153, v38
	v_fma_f32 v7, -v155, v22, v7
	v_fmac_f32_e32 v23, v155, v6
	v_cvt_pk_bf16_f32 v184, v39, v55
	v_cvt_pk_bf16_f32 v185, v7, v23
	ds_write_b32 v207, v184 offset:1360
	ds_write_b32 v207, v185 offset:1488
	v_fmac_f32_e32 v40, v152, v39
	v_fmac_f32_e32 v56, v152, v55
	v_fmac_f32_e32 v8, v154, v7
	v_fmac_f32_e32 v24, v154, v23
	v_fma_f32 v40, -v153, v55, v40
	v_fmac_f32_e32 v56, v153, v39
	v_fma_f32 v8, -v155, v23, v8
	v_fmac_f32_e32 v24, v155, v7
	v_cvt_pk_bf16_f32 v184, v40, v56
	v_cvt_pk_bf16_f32 v185, v8, v24
	ds_write_b32 v207, v184 offset:1632
	ds_write_b32 v207, v185 offset:1760
	v_fmac_f32_e32 v41, v152, v40
	v_fmac_f32_e32 v57, v152, v56
	v_fmac_f32_e32 v9, v154, v8
	v_fmac_f32_e32 v25, v154, v24
	v_fma_f32 v41, -v153, v56, v41
	v_fmac_f32_e32 v57, v153, v40
	v_fma_f32 v9, -v155, v24, v9
	v_fmac_f32_e32 v25, v155, v8
	v_cvt_pk_bf16_f32 v184, v41, v57
	v_cvt_pk_bf16_f32 v185, v9, v25
	ds_write_b32 v207, v184 offset:1904
	ds_write_b32 v207, v185 offset:2032
	v_fmac_f32_e32 v42, v152, v41
	v_fmac_f32_e32 v58, v152, v57
	v_fmac_f32_e32 v10, v154, v9
	v_fmac_f32_e32 v26, v154, v25
	v_fma_f32 v42, -v153, v57, v42
	v_fmac_f32_e32 v58, v153, v41
	v_fma_f32 v10, -v155, v25, v10
	v_fmac_f32_e32 v26, v155, v9
	v_cvt_pk_bf16_f32 v184, v42, v58
	v_cvt_pk_bf16_f32 v185, v10, v26
	ds_write_b32 v207, v184 offset:2176
	ds_write_b32 v207, v185 offset:2304
	v_fmac_f32_e32 v43, v152, v42
	v_fmac_f32_e32 v59, v152, v58
	v_fmac_f32_e32 v11, v154, v10
	v_fmac_f32_e32 v27, v154, v26
	v_fma_f32 v43, -v153, v58, v43
	v_fmac_f32_e32 v59, v153, v42
	v_fma_f32 v11, -v155, v26, v11
	v_fmac_f32_e32 v27, v155, v10
	v_cvt_pk_bf16_f32 v184, v43, v59
	v_cvt_pk_bf16_f32 v185, v11, v27
	ds_write_b32 v207, v184 offset:2448
	ds_write_b32 v207, v185 offset:2576
	v_fmac_f32_e32 v44, v152, v43
	v_fmac_f32_e32 v60, v152, v59
	v_fmac_f32_e32 v12, v154, v11
	v_fmac_f32_e32 v28, v154, v27
	v_fma_f32 v44, -v153, v59, v44
	v_fmac_f32_e32 v60, v153, v43
	v_fma_f32 v12, -v155, v27, v12
	v_fmac_f32_e32 v28, v155, v11
	v_cvt_pk_bf16_f32 v184, v44, v60
	v_cvt_pk_bf16_f32 v185, v12, v28
	ds_write_b32 v207, v184 offset:2720
	ds_write_b32 v207, v185 offset:2848
	v_fmac_f32_e32 v45, v152, v44
	v_fmac_f32_e32 v61, v152, v60
	v_fmac_f32_e32 v13, v154, v12
	v_fmac_f32_e32 v29, v154, v28
	v_fma_f32 v45, -v153, v60, v45
	v_fmac_f32_e32 v61, v153, v44
	v_fma_f32 v13, -v155, v28, v13
	v_fmac_f32_e32 v29, v155, v12
	v_cvt_pk_bf16_f32 v184, v45, v61
	v_cvt_pk_bf16_f32 v185, v13, v29
	ds_write_b32 v207, v184 offset:2992
	ds_write_b32 v207, v185 offset:3120
	v_fmac_f32_e32 v46, v152, v45
	v_fmac_f32_e32 v62, v152, v61
	v_fmac_f32_e32 v14, v154, v13
	v_fmac_f32_e32 v30, v154, v29
	v_fma_f32 v46, -v153, v61, v46
	v_fmac_f32_e32 v62, v153, v45
	v_fma_f32 v14, -v155, v29, v14
	v_fmac_f32_e32 v30, v155, v13
	v_cvt_pk_bf16_f32 v184, v46, v62
	v_cvt_pk_bf16_f32 v185, v14, v30
	ds_write_b32 v207, v184 offset:3264
	ds_write_b32 v207, v185 offset:3392
	v_fmac_f32_e32 v47, v152, v46
	v_fmac_f32_e32 v63, v152, v62
	v_fmac_f32_e32 v15, v154, v14
	v_fmac_f32_e32 v31, v154, v30
	v_fma_f32 v47, -v153, v62, v47
	v_fmac_f32_e32 v63, v153, v46
	v_fma_f32 v15, -v155, v30, v15
	v_fmac_f32_e32 v31, v155, v14
	v_cvt_pk_bf16_f32 v184, v47, v63
	v_cvt_pk_bf16_f32 v185, v15, v31
	ds_write_b32 v207, v184 offset:3536
	ds_write_b32 v207, v185 offset:3664
	v_fmac_f32_e32 v48, v152, v47
	v_fmac_f32_e32 v64, v152, v63
	v_fmac_f32_e32 v16, v154, v15
	v_fmac_f32_e32 v32, v154, v31
	v_fma_f32 v48, -v153, v63, v48
	v_fmac_f32_e32 v64, v153, v47
	v_fma_f32 v16, -v155, v31, v16
	v_fmac_f32_e32 v32, v155, v15
	v_cvt_pk_bf16_f32 v184, v48, v64
	v_cvt_pk_bf16_f32 v185, v16, v32
	ds_write_b32 v207, v184 offset:3808
	ds_write_b32 v207, v185 offset:3936
	v_fmac_f32_e32 v49, v152, v48
	v_fmac_f32_e32 v65, v152, v64
	v_fmac_f32_e32 v17, v154, v16
	v_fmac_f32_e32 v33, v154, v32
	v_fma_f32 v49, -v153, v64, v49
	v_fmac_f32_e32 v65, v153, v48
	v_fma_f32 v17, -v155, v32, v17
	v_fmac_f32_e32 v33, v155, v16
	v_cvt_pk_bf16_f32 v184, v49, v65
	v_cvt_pk_bf16_f32 v185, v17, v33
	ds_write_b32 v207, v184 offset:4080
	ds_write_b32 v207, v185 offset:4208
	v_mov_b32_e32 v182, v49
	v_mov_b32_e32 v178, v65
	v_mov_b32_e32 v180, v17
	v_mov_b32_e32 v176, v33
	s_branch .LBB0_99
.LBB0_106:
	s_or_b64 exec, exec, s[2:3]
	s_and_saveexec_b64 s[2:3], s[44:45]
	s_cbranch_execz .LBB0_91
	v_readlane_b32 s4, v251, 12
	v_readlane_b32 s5, v251, 13
	s_nop 1
	v_lshl_add_u64 v[2:3], v[150:151], 2, s[4:5]
	v_add_co_u32_e32 v4, vcc, 0x4000, v2
	global_store_dword v[2:3], v182, off
	s_nop 0
	v_addc_co_u32_e32 v5, vcc, 0, v3, vcc
	global_store_dword v[4:5], v178, off
	global_store_dword v[2:3], v180, off offset:128
	global_store_dword v[4:5], v176, off offset:128
	s_branch .LBB0_91
